# attention bodies: ring-base scalar math that lost its readers after slot specialisation removed (5 SALU per iteration), on top of the shortened loop-end ladder
# speedup vs baseline: 1.0005x; 1.0005x over previous
; #define SBAR() __builtin_amdgcn_sched_barrier(0)
; #define PK4(P, BASE, OUT) do { u32x4 w = {cvtpk(P[BASE + 0], P[BASE + 1]), cvtpk(P[BASE + 2], P[BASE + 3]), cvtpk(P[BASE + 4], P[BASE + 5]), cvtpk(P[BASE + 6], P[BASE + 7])}; \
;     OUT = *reinterpret_cast<bf16x8*>(&w); } while (0)
; __device__ __forceinline__ void finishSM(f32x16& p0, f32x16& p1, float alpha, float& l_reg, bf16x8& pa0, bf16x8& pa1, bf16x8& pa2, bf16x8& pa3) {
;   for (int r = 0; r < 16; ++r) p1[r] = __builtin_amdgcn_exp2f(p1[r]);
;   float ps = 0; for (int r = 0; r < 16; ++r) ps += p0[r]; for (int r = 0; r < 16; ++r) ps += p1[r];
;   asm volatile("" : "+v"(ps));
;   l_reg = l_reg * alpha + ps;
;     ...
;   PK4(p0, 0, pa0); PK4(p0, 8, pa1); PK4(p1, 0, pa2); PK4(p1, 8, pa3);
;     ...
; }
; __device__ __forceinline__ void qkt(f32x16& p0, f32x16& p1, const bf16* Ks, const bf16x8* qr, int r32, int hi) {
;   p0 = f32x16{}; p1 = f32x16{};
;   for (int d0 = 0; d0 < 8; ++d0) { int cb = (d0 * 16 + hi * 8) * 2;
;     bf16x8 b0 = *reinterpret_cast<const bf16x8*>((const char*)Ks + KSWZ(r32, cb));
;     bf16x8 b1 = *reinterpret_cast<const bf16x8*>((const char*)Ks + KSWZ(32 + r32, cb));
;     p0 = __builtin_amdgcn_mfma_f32_32x32x16_bf16(b0, qr[d0], p0, 0, 0, 0);
;     p1 = __builtin_amdgcn_mfma_f32_32x32x16_bf16(b1, qr[d0], p1, 0, 0, 0); }
; }
; template <typename TQ> ...
;     ...
;   for (int j = 1; j + 1 < NT; j += 2) {
;     SBAR(); qkt(pB0, pB1, (const bf16*)(K_lds + (j & 3) * (int)SHM_K), qr, r32, hi);
;     finishSM(pA0, pA1, alA, l_reg, pa0, pa1, pa2, pa3); SBAR();
;     DMA_TILE(j + 2, (j + 2) & 3); SBAR();
;     pv_d0(o, vb0 + ((j - 1) & 3) * (int)SHM_V, pa0, pa1, pa2, pa3); partialSM<true>(pB0, pB1, m_reg, mnB, alB);
.Lat461_a_in:
	s_mov_b32 s40, s33
	ds_read_b128 v[80:83], v178 offset:16384
	ds_read_b128 v[84:87], v178 offset:24576
	ds_read_b128 v[198:201], v179 offset:16384
	ds_read_b128 v[202:205], v179 offset:24576
	v_exp_f32_e32 v196, v96
	v_exp_f32_e32 v197, v97
	v_exp_f32_e32 v193, v98
	v_exp_f32_e32 v195, v99
	v_exp_f32_e32 v191, v100
	v_exp_f32_e32 v194, v101
	v_exp_f32_e32 v190, v102
	v_exp_f32_e32 v192, v103
	v_exp_f32_e32 v169, v104
	v_exp_f32_e32 v171, v105
	v_exp_f32_e32 v167, v106
	v_exp_f32_e32 v170, v107
	v_exp_f32_e32 v165, v108
	v_exp_f32_e32 v168, v109
	v_exp_f32_e32 v164, v110
	v_exp_f32_e32 v166, v111
.Lat461_a_go:
	s_waitcnt lgkmcnt(3)
	v_mfma_f32_32x32x16_bf16 v[96:111], v[80:83], v[136:139], 0
	v_exp_f32_e32 v238, v64
	v_add_f32_e32 v64, v197, v196
	v_add_f32_e32 v64, v193, v64
	v_add_f32_e32 v64, v195, v64
	s_waitcnt lgkmcnt(2)
	v_mfma_f32_32x32x16_bf16 v[80:95], v[84:87], v[136:139], 0
	v_add_f32_e32 v64, v191, v64
	v_add_f32_e32 v64, v194, v64
	v_add_f32_e32 v64, v190, v64
	v_add_f32_e32 v64, v192, v64
	v_add_f32_e32 v64, v169, v64
	v_add_f32_e32 v64, v171, v64
	s_waitcnt lgkmcnt(1)
	v_mfma_f32_32x32x16_bf16 v[96:111], v[198:201], v[140:143], v[96:111]
	v_add_f32_e32 v64, v167, v64
	v_add_f32_e32 v64, v170, v64
	v_add_f32_e32 v64, v165, v64
	v_add_f32_e32 v64, v168, v64
	v_add_f32_e32 v64, v164, v64
	v_add_f32_e32 v64, v166, v64
	v_exp_f32_e32 v239, v68
	s_waitcnt lgkmcnt(0)
	v_mfma_f32_32x32x16_bf16 v[80:95], v[202:205], v[140:143], v[80:95]
	ds_read_b128 v[198:201], v180 offset:16384
	ds_read_b128 v[202:205], v180 offset:24576
	v_add_f32_e32 v64, v238, v64
	v_exp_f32_e32 v240, v69
	v_exp_f32_e32 v241, v70
	v_exp_f32_e32 v242, v71
	s_waitcnt lgkmcnt(1)
	v_mfma_f32_32x32x16_bf16 v[96:111], v[198:201], v[132:135], v[96:111]
	ds_read_b128 v[198:201], v181 offset:16384
	ds_read_b128 v[206:209], v181 offset:24576
	ds_read_b128 v[210:213], v182 offset:16384
	ds_read_b128 v[214:217], v182 offset:24576
	ds_read_b128 v[218:221], v183 offset:16384
	ds_read_b128 v[222:225], v183 offset:24576
	v_exp_f32_e32 v243, v76
	v_exp_f32_e32 v244, v77
	v_exp_f32_e32 v245, v78
	v_exp_f32_e32 v79, v79
	s_waitcnt lgkmcnt(6)
	v_mfma_f32_32x32x16_bf16 v[80:95], v[202:205], v[132:135], v[80:95]
	ds_read_b128 v[202:205], v184 offset:16384
	ds_read_b128 v[226:229], v184 offset:24576
	ds_read_b128 v[230:233], v185 offset:16384
	ds_read_b128 v[234:237], v185 offset:24576
	s_waitcnt lgkmcnt(9)
	v_mfma_f32_32x32x16_bf16 v[96:111], v[198:201], v[128:131], v[96:111]
	v_exp_f32_e32 v199, v65
	v_exp_f32_e32 v200, v66
	v_exp_f32_e32 v201, v67
	v_add_f32_e32 v64, v199, v64
	v_add_f32_e32 v64, v200, v64
	v_add_f32_e32 v64, v201, v64
	s_waitcnt lgkmcnt(8)
	v_mfma_f32_32x32x16_bf16 v[80:95], v[206:209], v[128:131], v[80:95]
	v_exp_f32_e32 v206, v72
	v_add_f32_e32 v64, v239, v64
	v_exp_f32_e32 v207, v73
	v_add_f32_e32 v64, v240, v64
	v_exp_f32_e32 v208, v74
	v_add_f32_e32 v64, v241, v64
	v_exp_f32_e32 v209, v75
	s_waitcnt lgkmcnt(7)
	v_mfma_f32_32x32x16_bf16 v[96:111], v[210:213], v[124:127], v[96:111]
	v_add_f32_e32 v64, v242, v64
	v_add_f32_e32 v64, v206, v64
	v_add_f32_e32 v64, v207, v64
	v_add_f32_e32 v64, v208, v64
	v_add_f32_e32 v64, v209, v64
	v_add_f32_e32 v64, v243, v64
	v_add_f32_e32 v64, v244, v64
	s_waitcnt lgkmcnt(6)
	v_mfma_f32_32x32x16_bf16 v[80:95], v[214:217], v[124:127], v[80:95]
	v_add_f32_e32 v64, v245, v64
	v_add_f32_e32 v198, v79, v64
	v_cvt_pk_bf16_f32 v64, v196, v197
	v_cvt_pk_bf16_f32 v65, v193, v195
	v_cvt_pk_bf16_f32 v66, v191, v194
	v_cvt_pk_bf16_f32 v67, v190, v192
	s_waitcnt lgkmcnt(5)
	v_mfma_f32_32x32x16_bf16 v[96:111], v[218:221], v[120:123], v[96:111]
	v_cvt_pk_bf16_f32 v68, v169, v171
	v_cvt_pk_bf16_f32 v69, v167, v170
	v_cvt_pk_bf16_f32 v70, v165, v168
	v_cvt_pk_bf16_f32 v71, v164, v166
	v_cvt_pk_bf16_f32 v72, v238, v199
	v_cvt_pk_bf16_f32 v73, v200, v201
	v_cvt_pk_bf16_f32 v74, v239, v240
	s_waitcnt lgkmcnt(4)
	v_mfma_f32_32x32x16_bf16 v[80:95], v[222:225], v[120:123], v[80:95]
	v_cvt_pk_bf16_f32 v75, v241, v242
	v_cvt_pk_bf16_f32 v76, v206, v207
	v_cvt_pk_bf16_f32 v77, v208, v209
	v_cvt_pk_bf16_f32 v78, v243, v244
	v_cvt_pk_bf16_f32 v79, v245, v79
	s_waitcnt lgkmcnt(3)
	v_mfma_f32_32x32x16_bf16 v[96:111], v[202:205], v[116:119], v[96:111]
	s_add_i32 s33, s40, 0x8000
	s_and_b32 s43, s33, 0xc000
	ds_read_b64_tr_b16 v[190:191], v176
	ds_read_b64_tr_b16 v[192:193], v176 offset:2048
	ds_read_b64_tr_b16 v[194:195], v176 offset:4096
	ds_read_b64_tr_b16 v[196:197], v176 offset:6144
	s_waitcnt lgkmcnt(6)
	v_mfma_f32_32x32x16_bf16 v[80:95], v[226:229], v[116:119], v[80:95]
	ds_read_b64_tr_b16 v[200:201], v176 offset:8192
	ds_read_b64_tr_b16 v[202:203], v176 offset:10240
	ds_read_b64_tr_b16 v[204:205], v176 offset:12288
	ds_read_b64_tr_b16 v[206:207], v176 offset:14336
	s_add_i32 s74, s40, 0x4000
	s_and_b32 s74, s74, 0xc000
	s_add_u32 s98, s38, s22
	s_addc_u32 s99, s39, s23
	s_add_i32 s41, s67, s74
	s_add_u32 s100, s38, s24
	s_addc_u32 s101, s39, s25
	s_mov_b32 m0, s41
	s_add_i32 s74, s72, s74
	global_load_lds_dwordx4 v156, s[98:99]
	s_waitcnt lgkmcnt(9)
	v_mfma_f32_32x32x16_bf16 v[96:111], v[230:233], v[112:115], v[96:111]
	s_add_i32 m0, s41, 0x2000
	s_nop 0
	global_load_lds_dwordx4 v158, s[98:99]
	s_mov_b32 m0, s74
	s_nop 0
	global_load_lds_dwordx4 v162, s[100:101]
	s_waitcnt lgkmcnt(8)
; #define SBAR() __builtin_amdgcn_sched_barrier(0)
; #define PUBLISH(n) do { asm volatile("s_waitcnt vmcnt(" #n ")" ::: "memory"); asm volatile("s_waitcnt lgkmcnt(0)" ::: "memory"); __builtin_amdgcn_s_barrier(); SBAR(); } while (0)
; template <int D0> __device__ __forceinline__ void pv_one(f32x16& od, int vb, bf16x8 pa0, bf16x8 pa1, bf16x8 pa2, bf16x8 pa3) {
;   const s16x4 l0 = tr_read<v_rd_off(D0, 0, 0)>(vb), h0 = tr_read<v_rd_off(D0, 0, 1)>(vb), l1 = tr_read<v_rd_off(D0, 1, 0)>(vb), h1 = tr_read<v_rd_off(D0, 1, 1)>(vb);
;   const s16x4 l2 = tr_read<v_rd_off(D0, 2, 0)>(vb), h2 = tr_read<v_rd_off(D0, 2, 1)>(vb), l3 = tr_read<v_rd_off(D0, 3, 0)>(vb), h3 = tr_read<v_rd_off(D0, 3, 1)>(vb);
;   asm volatile("s_waitcnt lgkmcnt(0)" ::: "memory"); SBAR();
;     ...
;   od = __builtin_amdgcn_mfma_f32_32x32x16_bf16(pa0, PK(l0, h0), od, 0, 0, 0);
;   od = __builtin_amdgcn_mfma_f32_32x32x16_bf16(pa1, PK(l1, h1), od, 0, 0, 0);
;   od = __builtin_amdgcn_mfma_f32_32x32x16_bf16(pa2, PK(l2, h2), od, 0, 0, 0);
;   od = __builtin_amdgcn_mfma_f32_32x32x16_bf16(pa3, PK(l3, h3), od, 0, 0, 0);
;     ...
; }
; __device__ __forceinline__ void pv_d0(f32x16* o, int vb, bf16x8 pa0, bf16x8 pa1, bf16x8 pa2, bf16x8 pa3) {
;   pv_one<0>(o[0], vb, pa0, pa1, pa2, pa3); pv_one<1>(o[1], vb, pa0, pa1, pa2, pa3); pv_one<2>(o[2], vb, pa0, pa1, pa2, pa3); pv_one<3>(o[3], vb, pa0, pa1, pa2, pa3);
; }
; template <typename TQ> ...
;     ...
;   for (int j = 1; j + 1 < NT; j += 2) {
;     SBAR(); qkt(pB0, pB1, (const bf16*)(K_lds + (j & 3) * (int)SHM_K), qr, r32, hi);
;     finishSM(pA0, pA1, alA, l_reg, pa0, pa1, pa2, pa3); SBAR();
;     DMA_TILE(j + 2, (j + 2) & 3); SBAR();
;     pv_d0(o, vb0 + ((j - 1) & 3) * (int)SHM_V, pa0, pa1, pa2, pa3); partialSM<true>(pB0, pB1, m_reg, mnB, alB);
;     PUBLISH(4);
;     SBAR(); qkt(pA0, pA1, (const bf16*)(K_lds + ((j + 1) & 3) * (int)SHM_K), qr, r32, hi);
;     finishSM(pB0, pB1, alB, l_reg, pa0, pa1, pa2, pa3); SBAR();
;     if (j + 3 < NT) { DMA_TILE(j + 3, (j + 3) & 3); } SBAR();
	v_mfma_f32_32x32x16_bf16 v[80:95], v[234:237], v[112:115], v[80:95]
	s_add_i32 m0, s74, 0x2000
	s_nop 0
	global_load_lds_dwordx4 v160, s[100:101]
	s_nop 0
	s_waitcnt lgkmcnt(6)
	v_mfma_f32_32x32x16_bf16 v[48:63], v[64:67], v[190:193], v[48:63]
	v_exp_f32_e32 v232, v96
	ds_read_b64_tr_b16 v[190:191], v176 offset:512
	ds_read_b64_tr_b16 v[192:193], v176 offset:2560
	s_waitcnt lgkmcnt(6)
	v_mfma_f32_32x32x16_bf16 v[48:63], v[68:71], v[194:197], v[48:63]
	v_exp_f32_e32 v233, v97
	ds_read_b64_tr_b16 v[194:195], v176 offset:4608
	ds_read_b64_tr_b16 v[196:197], v176 offset:6656
	s_waitcnt lgkmcnt(6)
	v_mfma_f32_32x32x16_bf16 v[48:63], v[72:75], v[200:203], v[48:63]
	v_exp_f32_e32 v234, v98
	ds_read_b64_tr_b16 v[200:201], v176 offset:8704
	ds_read_b64_tr_b16 v[202:203], v176 offset:10752
	ds_read_b64_tr_b16 v[208:209], v176 offset:12800
	ds_read_b64_tr_b16 v[210:211], v176 offset:14848
	s_waitcnt lgkmcnt(8)
	v_mfma_f32_32x32x16_bf16 v[48:63], v[76:79], v[204:207], v[48:63]
	v_exp_f32_e32 v235, v99
	s_waitcnt lgkmcnt(6)
	v_mfma_f32_32x32x16_bf16 v[32:47], v[64:67], v[190:193], v[32:47]
	v_exp_f32_e32 v236, v100
	ds_read_b64_tr_b16 v[190:191], v176 offset:1024
	ds_read_b64_tr_b16 v[192:193], v176 offset:3072
	s_waitcnt lgkmcnt(6)
	v_mfma_f32_32x32x16_bf16 v[32:47], v[68:71], v[194:197], v[32:47]
	v_exp_f32_e32 v237, v101
	ds_read_b64_tr_b16 v[194:195], v176 offset:5120
	ds_read_b64_tr_b16 v[196:197], v176 offset:7168
	s_waitcnt lgkmcnt(6)
	v_mfma_f32_32x32x16_bf16 v[32:47], v[72:75], v[200:203], v[32:47]
	v_exp_f32_e32 v238, v102
	ds_read_b64_tr_b16 v[200:201], v176 offset:9216
	ds_read_b64_tr_b16 v[202:203], v176 offset:11264
	ds_read_b64_tr_b16 v[204:205], v176 offset:13312
	ds_read_b64_tr_b16 v[206:207], v176 offset:15360
	s_waitcnt lgkmcnt(8)
	v_mfma_f32_32x32x16_bf16 v[32:47], v[76:79], v[208:211], v[32:47]
	v_exp_f32_e32 v239, v103
	v_exp_f32_e32 v240, v104
	s_waitcnt lgkmcnt(6)
	v_mfma_f32_32x32x16_bf16 v[16:31], v[64:67], v[190:193], v[16:31]
	v_exp_f32_e32 v241, v105
	ds_read_b64_tr_b16 v[190:191], v176 offset:1536
	ds_read_b64_tr_b16 v[192:193], v176 offset:3584
	s_waitcnt lgkmcnt(6)
	v_mfma_f32_32x32x16_bf16 v[16:31], v[68:71], v[194:197], v[16:31]
	v_exp_f32_e32 v242, v106
	ds_read_b64_tr_b16 v[194:195], v176 offset:5632
	ds_read_b64_tr_b16 v[196:197], v176 offset:7680
	s_waitcnt lgkmcnt(6)
	v_mfma_f32_32x32x16_bf16 v[16:31], v[72:75], v[200:203], v[16:31]
	v_exp_f32_e32 v243, v107
	ds_read_b64_tr_b16 v[200:201], v176 offset:9728
	ds_read_b64_tr_b16 v[202:203], v176 offset:11776
	ds_read_b64_tr_b16 v[208:209], v176 offset:13824
	ds_read_b64_tr_b16 v[210:211], v176 offset:15872
	s_waitcnt lgkmcnt(8)
	v_mfma_f32_32x32x16_bf16 v[16:31], v[76:79], v[204:207], v[16:31]
	v_exp_f32_e32 v244, v108
	s_waitcnt lgkmcnt(6)
	v_mfma_f32_32x32x16_bf16 v[0:15], v[64:67], v[190:193], v[0:15]
	v_exp_f32_e32 v245, v109
	s_waitcnt lgkmcnt(4)
	v_mfma_f32_32x32x16_bf16 v[0:15], v[68:71], v[194:197], v[0:15]
	v_exp_f32_e32 v246, v110
	s_waitcnt lgkmcnt(2)
	v_mfma_f32_32x32x16_bf16 v[0:15], v[72:75], v[200:203], v[0:15]
	v_exp_f32_e32 v247, v111
	s_waitcnt vmcnt(4)
	s_waitcnt lgkmcnt(0)
	s_barrier
	v_mfma_f32_32x32x16_bf16 v[0:15], v[76:79], v[208:211], v[0:15]
	ds_read_b128 v[64:67], v178 offset:32768
	ds_read_b128 v[68:71], v178 offset:40960
	ds_read_b128 v[190:193], v179 offset:32768
	ds_read_b128 v[194:197], v179 offset:40960
	s_waitcnt lgkmcnt(3)
	v_mfma_f32_32x32x16_bf16 v[96:111], v[64:67], v[136:139], 0
	v_exp_f32_e32 v80, v80
	v_exp_f32_e32 v81, v81
	v_exp_f32_e32 v82, v82
	v_exp_f32_e32 v83, v83
	v_exp_f32_e32 v87, v87
	v_exp_f32_e32 v248, v93
	v_exp_f32_e32 v249, v94
	s_waitcnt lgkmcnt(2)
	v_mfma_f32_32x32x16_bf16 v[64:79], v[68:71], v[136:139], 0
	s_waitcnt lgkmcnt(1)
	v_mfma_f32_32x32x16_bf16 v[96:111], v[190:193], v[140:143], v[96:111]
	s_waitcnt lgkmcnt(0)
	v_mfma_f32_32x32x16_bf16 v[64:79], v[194:197], v[140:143], v[64:79]
	ds_read_b128 v[190:193], v180 offset:32768
	ds_read_b128 v[194:197], v180 offset:40960
	s_waitcnt lgkmcnt(1)
	v_mfma_f32_32x32x16_bf16 v[96:111], v[190:193], v[132:135], v[96:111]
	ds_read_b128 v[190:193], v181 offset:32768
	ds_read_b128 v[200:203], v181 offset:40960
	ds_read_b128 v[204:207], v182 offset:32768
	ds_read_b128 v[208:211], v182 offset:40960
	ds_read_b128 v[212:215], v183 offset:32768
	ds_read_b128 v[216:219], v183 offset:40960
	s_waitcnt lgkmcnt(6)
	v_mfma_f32_32x32x16_bf16 v[64:79], v[194:197], v[132:135], v[64:79]
	ds_read_b128 v[194:197], v184 offset:32768
	ds_read_b128 v[220:223], v184 offset:40960
	ds_read_b128 v[224:227], v185 offset:32768
	ds_read_b128 v[228:231], v185 offset:40960
	s_waitcnt lgkmcnt(9)
	v_mfma_f32_32x32x16_bf16 v[96:111], v[190:193], v[128:131], v[96:111]
	s_cmp_ge_u32 s73, s37
	s_cselect_b64 s[40:41], -1, 0
	s_and_b64 vcc, exec, s[40:41]
	s_cbranch_vccnz .LBB0_463
	s_add_i32 s74, s67, s43
	s_add_u32 s98, s38, s26
	s_addc_u32 s99, s39, s27
	s_mov_b32 m0, s74
	s_add_i32 s43, s72, s43
	global_load_lds_dwordx4 v156, s[98:99]
	s_add_u32 s100, s38, s28
	s_addc_u32 s101, s39, s29
	s_add_i32 m0, s74, 0x2000
	s_nop 0
	global_load_lds_dwordx4 v158, s[98:99]
	s_mov_b32 m0, s43
	s_nop 0
	global_load_lds_dwordx4 v162, s[100:101]
	s_add_i32 m0, s43, 0x2000
	s_nop 0
	global_load_lds_dwordx4 v160, s[100:101]

; #define SBAR() __builtin_amdgcn_sched_barrier(0)
; #define PK4(P, BASE, OUT) do { u32x4 w = {cvtpk(P[BASE + 0], P[BASE + 1]), cvtpk(P[BASE + 2], P[BASE + 3]), cvtpk(P[BASE + 4], P[BASE + 5]), cvtpk(P[BASE + 6], P[BASE + 7])}; \
;     OUT = *reinterpret_cast<bf16x8*>(&w); } while (0)
; __device__ __forceinline__ void finishSM(f32x16& p0, f32x16& p1, float alpha, float& l_reg, bf16x8& pa0, bf16x8& pa1, bf16x8& pa2, bf16x8& pa3) {
;   for (int r = 0; r < 16; ++r) p1[r] = __builtin_amdgcn_exp2f(p1[r]);
;   float ps = 0; for (int r = 0; r < 16; ++r) ps += p0[r]; for (int r = 0; r < 16; ++r) ps += p1[r];
;   asm volatile("" : "+v"(ps));
;   l_reg = l_reg * alpha + ps;
;     ...
;   PK4(p0, 0, pa0); PK4(p0, 8, pa1); PK4(p1, 0, pa2); PK4(p1, 8, pa3);
;     ...
; }
; __device__ __forceinline__ void qkt(f32x16& p0, f32x16& p1, const bf16* Ks, const bf16x8* qr, int r32, int hi) {
;   p0 = f32x16{}; p1 = f32x16{};
;   for (int d0 = 0; d0 < 8; ++d0) { int cb = (d0 * 16 + hi * 8) * 2;
;     bf16x8 b0 = *reinterpret_cast<const bf16x8*>((const char*)Ks + KSWZ(r32, cb));
;     bf16x8 b1 = *reinterpret_cast<const bf16x8*>((const char*)Ks + KSWZ(32 + r32, cb));
;     p0 = __builtin_amdgcn_mfma_f32_32x32x16_bf16(b0, qr[d0], p0, 0, 0, 0);
;     p1 = __builtin_amdgcn_mfma_f32_32x32x16_bf16(b1, qr[d0], p1, 0, 0, 0); }
; }
; template <typename TQ> ...
;     ...
;   for (int j = 1; j + 1 < NT; j += 2) {
;     SBAR(); qkt(pB0, pB1, (const bf16*)(K_lds + (j & 3) * (int)SHM_K), qr, r32, hi);
;     finishSM(pA0, pA1, alA, l_reg, pa0, pa1, pa2, pa3); SBAR();
;     DMA_TILE(j + 2, (j + 2) & 3); SBAR();
;     pv_d0(o, vb0 + ((j - 1) & 3) * (int)SHM_V, pa0, pa1, pa2, pa3); partialSM<true>(pB0, pB1, m_reg, mnB, alB);
.Lat461_b:
.Lat461_b_in:
	s_mov_b32 s40, s33
	ds_read_b128 v[80:83], v178 offset:49152
	ds_read_b128 v[84:87], v178 offset:57344
	ds_read_b128 v[198:201], v179 offset:49152
	ds_read_b128 v[202:205], v179 offset:57344
	v_exp_f32_e32 v196, v96
	v_exp_f32_e32 v197, v97
	v_exp_f32_e32 v193, v98
	v_exp_f32_e32 v195, v99
	v_exp_f32_e32 v191, v100
	v_exp_f32_e32 v194, v101
	v_exp_f32_e32 v190, v102
	v_exp_f32_e32 v192, v103
	v_exp_f32_e32 v169, v104
	v_exp_f32_e32 v171, v105
	v_exp_f32_e32 v167, v106
	v_exp_f32_e32 v170, v107
	v_exp_f32_e32 v165, v108
	v_exp_f32_e32 v168, v109
	v_exp_f32_e32 v164, v110
	v_exp_f32_e32 v166, v111
	s_waitcnt lgkmcnt(3)
	v_mfma_f32_32x32x16_bf16 v[96:111], v[80:83], v[136:139], 0
	v_exp_f32_e32 v238, v64
	v_add_f32_e32 v64, v197, v196
	v_add_f32_e32 v64, v193, v64
	v_add_f32_e32 v64, v195, v64
	s_waitcnt lgkmcnt(2)
	v_mfma_f32_32x32x16_bf16 v[80:95], v[84:87], v[136:139], 0
	v_add_f32_e32 v64, v191, v64
	v_add_f32_e32 v64, v194, v64
	v_add_f32_e32 v64, v190, v64
	v_add_f32_e32 v64, v192, v64
	v_add_f32_e32 v64, v169, v64
	v_add_f32_e32 v64, v171, v64
	s_waitcnt lgkmcnt(1)
	v_mfma_f32_32x32x16_bf16 v[96:111], v[198:201], v[140:143], v[96:111]
	v_add_f32_e32 v64, v167, v64
	v_add_f32_e32 v64, v170, v64
	v_add_f32_e32 v64, v165, v64
	v_add_f32_e32 v64, v168, v64
	v_add_f32_e32 v64, v164, v64
	v_add_f32_e32 v64, v166, v64
	v_exp_f32_e32 v239, v68
	s_waitcnt lgkmcnt(0)
	v_mfma_f32_32x32x16_bf16 v[80:95], v[202:205], v[140:143], v[80:95]
	ds_read_b128 v[198:201], v180 offset:49152
	ds_read_b128 v[202:205], v180 offset:57344
	v_add_f32_e32 v64, v238, v64
	v_exp_f32_e32 v240, v69
	v_exp_f32_e32 v241, v70
	v_exp_f32_e32 v242, v71
	s_waitcnt lgkmcnt(1)
	v_mfma_f32_32x32x16_bf16 v[96:111], v[198:201], v[132:135], v[96:111]
	ds_read_b128 v[198:201], v181 offset:49152
	ds_read_b128 v[206:209], v181 offset:57344
	ds_read_b128 v[210:213], v182 offset:49152
	ds_read_b128 v[214:217], v182 offset:57344
	ds_read_b128 v[218:221], v183 offset:49152
	ds_read_b128 v[222:225], v183 offset:57344
	v_exp_f32_e32 v243, v76
	v_exp_f32_e32 v244, v77
	v_exp_f32_e32 v245, v78
	v_exp_f32_e32 v79, v79
	s_waitcnt lgkmcnt(6)
	v_mfma_f32_32x32x16_bf16 v[80:95], v[202:205], v[132:135], v[80:95]
	ds_read_b128 v[202:205], v184 offset:49152
	ds_read_b128 v[226:229], v184 offset:57344
	ds_read_b128 v[230:233], v185 offset:49152
	ds_read_b128 v[234:237], v185 offset:57344
	s_waitcnt lgkmcnt(9)
	v_mfma_f32_32x32x16_bf16 v[96:111], v[198:201], v[128:131], v[96:111]
	v_exp_f32_e32 v199, v65
	v_exp_f32_e32 v200, v66
	v_exp_f32_e32 v201, v67
	v_add_f32_e32 v64, v199, v64
	v_add_f32_e32 v64, v200, v64
	v_add_f32_e32 v64, v201, v64
	s_waitcnt lgkmcnt(8)
	v_mfma_f32_32x32x16_bf16 v[80:95], v[206:209], v[128:131], v[80:95]
	v_exp_f32_e32 v206, v72
	v_add_f32_e32 v64, v239, v64
	v_exp_f32_e32 v207, v73
	v_add_f32_e32 v64, v240, v64
	v_exp_f32_e32 v208, v74
	v_add_f32_e32 v64, v241, v64
	v_exp_f32_e32 v209, v75
	s_waitcnt lgkmcnt(7)
	v_mfma_f32_32x32x16_bf16 v[96:111], v[210:213], v[124:127], v[96:111]
	v_add_f32_e32 v64, v242, v64
	v_add_f32_e32 v64, v206, v64
	v_add_f32_e32 v64, v207, v64
	v_add_f32_e32 v64, v208, v64
	v_add_f32_e32 v64, v209, v64
	v_add_f32_e32 v64, v243, v64
	v_add_f32_e32 v64, v244, v64
	s_waitcnt lgkmcnt(6)
	v_mfma_f32_32x32x16_bf16 v[80:95], v[214:217], v[124:127], v[80:95]
	v_add_f32_e32 v64, v245, v64
	v_add_f32_e32 v198, v79, v64
	v_cvt_pk_bf16_f32 v64, v196, v197
	v_cvt_pk_bf16_f32 v65, v193, v195
	v_cvt_pk_bf16_f32 v66, v191, v194
	v_cvt_pk_bf16_f32 v67, v190, v192
	s_waitcnt lgkmcnt(5)
	v_mfma_f32_32x32x16_bf16 v[96:111], v[218:221], v[120:123], v[96:111]
	v_cvt_pk_bf16_f32 v68, v169, v171
	v_cvt_pk_bf16_f32 v69, v167, v170
	v_cvt_pk_bf16_f32 v70, v165, v168
	v_cvt_pk_bf16_f32 v71, v164, v166
	v_cvt_pk_bf16_f32 v72, v238, v199
	v_cvt_pk_bf16_f32 v73, v200, v201
	v_cvt_pk_bf16_f32 v74, v239, v240
	s_waitcnt lgkmcnt(4)
	v_mfma_f32_32x32x16_bf16 v[80:95], v[222:225], v[120:123], v[80:95]
	v_cvt_pk_bf16_f32 v75, v241, v242
	v_cvt_pk_bf16_f32 v76, v206, v207
	v_cvt_pk_bf16_f32 v77, v208, v209
	v_cvt_pk_bf16_f32 v78, v243, v244
	v_cvt_pk_bf16_f32 v79, v245, v79
	s_waitcnt lgkmcnt(3)
	v_mfma_f32_32x32x16_bf16 v[96:111], v[202:205], v[116:119], v[96:111]
	s_add_i32 s33, s40, 0x8000
	s_and_b32 s43, s33, 0xc000
	ds_read_b64_tr_b16 v[190:191], v176 offset:32768
	ds_read_b64_tr_b16 v[192:193], v176 offset:34816
	ds_read_b64_tr_b16 v[194:195], v176 offset:36864
	ds_read_b64_tr_b16 v[196:197], v176 offset:38912
	s_waitcnt lgkmcnt(6)
	v_mfma_f32_32x32x16_bf16 v[80:95], v[226:229], v[116:119], v[80:95]
	ds_read_b64_tr_b16 v[200:201], v176 offset:40960
	ds_read_b64_tr_b16 v[202:203], v176 offset:43008
	ds_read_b64_tr_b16 v[204:205], v176 offset:45056
	ds_read_b64_tr_b16 v[206:207], v176 offset:47104
	s_add_i32 s74, s40, 0x4000
	s_and_b32 s74, s74, 0xc000
	s_add_u32 s98, s38, s22
	s_addc_u32 s99, s39, s23
	s_add_i32 s41, s67, s74
	s_add_u32 s100, s38, s24
	s_addc_u32 s101, s39, s25
	s_mov_b32 m0, s41
	s_add_i32 s74, s72, s74
	global_load_lds_dwordx4 v156, s[98:99]
	s_waitcnt lgkmcnt(9)
; #define SBAR() __builtin_amdgcn_sched_barrier(0)
; #define PUBLISH(n) do { asm volatile("s_waitcnt vmcnt(" #n ")" ::: "memory"); asm volatile("s_waitcnt lgkmcnt(0)" ::: "memory"); __builtin_amdgcn_s_barrier(); SBAR(); } while (0)
; template <int D0> __device__ __forceinline__ void pv_one(f32x16& od, int vb, bf16x8 pa0, bf16x8 pa1, bf16x8 pa2, bf16x8 pa3) {
;   const s16x4 l0 = tr_read<v_rd_off(D0, 0, 0)>(vb), h0 = tr_read<v_rd_off(D0, 0, 1)>(vb), l1 = tr_read<v_rd_off(D0, 1, 0)>(vb), h1 = tr_read<v_rd_off(D0, 1, 1)>(vb);
;   const s16x4 l2 = tr_read<v_rd_off(D0, 2, 0)>(vb), h2 = tr_read<v_rd_off(D0, 2, 1)>(vb), l3 = tr_read<v_rd_off(D0, 3, 0)>(vb), h3 = tr_read<v_rd_off(D0, 3, 1)>(vb);
;   asm volatile("s_waitcnt lgkmcnt(0)" ::: "memory"); SBAR();
;     ...
;   od = __builtin_amdgcn_mfma_f32_32x32x16_bf16(pa0, PK(l0, h0), od, 0, 0, 0);
;   od = __builtin_amdgcn_mfma_f32_32x32x16_bf16(pa1, PK(l1, h1), od, 0, 0, 0);
;   od = __builtin_amdgcn_mfma_f32_32x32x16_bf16(pa2, PK(l2, h2), od, 0, 0, 0);
;   od = __builtin_amdgcn_mfma_f32_32x32x16_bf16(pa3, PK(l3, h3), od, 0, 0, 0);
;     ...
; }
; __device__ __forceinline__ void pv_d0(f32x16* o, int vb, bf16x8 pa0, bf16x8 pa1, bf16x8 pa2, bf16x8 pa3) {
;   pv_one<0>(o[0], vb, pa0, pa1, pa2, pa3); pv_one<1>(o[1], vb, pa0, pa1, pa2, pa3); pv_one<2>(o[2], vb, pa0, pa1, pa2, pa3); pv_one<3>(o[3], vb, pa0, pa1, pa2, pa3);
; }
; template <typename TQ> ...
;     ...
;   for (int j = 1; j + 1 < NT; j += 2) {
;     SBAR(); qkt(pB0, pB1, (const bf16*)(K_lds + (j & 3) * (int)SHM_K), qr, r32, hi);
;     finishSM(pA0, pA1, alA, l_reg, pa0, pa1, pa2, pa3); SBAR();
;     DMA_TILE(j + 2, (j + 2) & 3); SBAR();
;     pv_d0(o, vb0 + ((j - 1) & 3) * (int)SHM_V, pa0, pa1, pa2, pa3); partialSM<true>(pB0, pB1, m_reg, mnB, alB);
;     PUBLISH(4);
;     SBAR(); qkt(pA0, pA1, (const bf16*)(K_lds + ((j + 1) & 3) * (int)SHM_K), qr, r32, hi);
;     finishSM(pB0, pB1, alB, l_reg, pa0, pa1, pa2, pa3); SBAR();
;     if (j + 3 < NT) { DMA_TILE(j + 3, (j + 3) & 3); } SBAR();
	v_mfma_f32_32x32x16_bf16 v[96:111], v[230:233], v[112:115], v[96:111]
	s_add_i32 m0, s41, 0x2000
	s_nop 0
	global_load_lds_dwordx4 v158, s[98:99]
	s_mov_b32 m0, s74
	s_nop 0
	global_load_lds_dwordx4 v162, s[100:101]
	s_waitcnt lgkmcnt(8)
	v_mfma_f32_32x32x16_bf16 v[80:95], v[234:237], v[112:115], v[80:95]
	s_add_i32 m0, s74, 0x2000
	s_nop 0
	global_load_lds_dwordx4 v160, s[100:101]
	s_nop 0
	s_waitcnt lgkmcnt(6)
	v_mfma_f32_32x32x16_bf16 v[48:63], v[64:67], v[190:193], v[48:63]
	v_exp_f32_e32 v232, v96
	ds_read_b64_tr_b16 v[190:191], v176 offset:33280
	ds_read_b64_tr_b16 v[192:193], v176 offset:35328
	s_waitcnt lgkmcnt(6)
	v_mfma_f32_32x32x16_bf16 v[48:63], v[68:71], v[194:197], v[48:63]
	v_exp_f32_e32 v233, v97
	ds_read_b64_tr_b16 v[194:195], v176 offset:37376
	ds_read_b64_tr_b16 v[196:197], v176 offset:39424
	s_waitcnt lgkmcnt(6)
	v_mfma_f32_32x32x16_bf16 v[48:63], v[72:75], v[200:203], v[48:63]
	v_exp_f32_e32 v234, v98
	ds_read_b64_tr_b16 v[200:201], v176 offset:41472
	ds_read_b64_tr_b16 v[202:203], v176 offset:43520
	ds_read_b64_tr_b16 v[208:209], v176 offset:45568
	ds_read_b64_tr_b16 v[210:211], v176 offset:47616
	s_waitcnt lgkmcnt(8)
	v_mfma_f32_32x32x16_bf16 v[48:63], v[76:79], v[204:207], v[48:63]
	v_exp_f32_e32 v235, v99
	s_waitcnt lgkmcnt(6)
	v_mfma_f32_32x32x16_bf16 v[32:47], v[64:67], v[190:193], v[32:47]
	v_exp_f32_e32 v236, v100
	ds_read_b64_tr_b16 v[190:191], v176 offset:33792
	ds_read_b64_tr_b16 v[192:193], v176 offset:35840
	s_waitcnt lgkmcnt(6)
	v_mfma_f32_32x32x16_bf16 v[32:47], v[68:71], v[194:197], v[32:47]
	v_exp_f32_e32 v237, v101
	ds_read_b64_tr_b16 v[194:195], v176 offset:37888
	ds_read_b64_tr_b16 v[196:197], v176 offset:39936
	s_waitcnt lgkmcnt(6)
	v_mfma_f32_32x32x16_bf16 v[32:47], v[72:75], v[200:203], v[32:47]
	v_exp_f32_e32 v238, v102
	ds_read_b64_tr_b16 v[200:201], v176 offset:41984
	ds_read_b64_tr_b16 v[202:203], v176 offset:44032
	ds_read_b64_tr_b16 v[204:205], v176 offset:46080
	ds_read_b64_tr_b16 v[206:207], v176 offset:48128
	s_waitcnt lgkmcnt(8)
	v_mfma_f32_32x32x16_bf16 v[32:47], v[76:79], v[208:211], v[32:47]
	v_exp_f32_e32 v239, v103
	v_exp_f32_e32 v240, v104
	s_waitcnt lgkmcnt(6)
	v_mfma_f32_32x32x16_bf16 v[16:31], v[64:67], v[190:193], v[16:31]
	v_exp_f32_e32 v241, v105
	ds_read_b64_tr_b16 v[190:191], v176 offset:34304
	ds_read_b64_tr_b16 v[192:193], v176 offset:36352
	s_waitcnt lgkmcnt(6)
	v_mfma_f32_32x32x16_bf16 v[16:31], v[68:71], v[194:197], v[16:31]
	v_exp_f32_e32 v242, v106
	ds_read_b64_tr_b16 v[194:195], v176 offset:38400
	ds_read_b64_tr_b16 v[196:197], v176 offset:40448
	s_waitcnt lgkmcnt(6)
	v_mfma_f32_32x32x16_bf16 v[16:31], v[72:75], v[200:203], v[16:31]
	v_exp_f32_e32 v243, v107
	ds_read_b64_tr_b16 v[200:201], v176 offset:42496
	ds_read_b64_tr_b16 v[202:203], v176 offset:44544
	ds_read_b64_tr_b16 v[208:209], v176 offset:46592
	ds_read_b64_tr_b16 v[210:211], v176 offset:48640
	s_waitcnt lgkmcnt(8)
	v_mfma_f32_32x32x16_bf16 v[16:31], v[76:79], v[204:207], v[16:31]
	v_exp_f32_e32 v244, v108
	s_waitcnt lgkmcnt(6)
	v_mfma_f32_32x32x16_bf16 v[0:15], v[64:67], v[190:193], v[0:15]
	v_exp_f32_e32 v245, v109
	s_waitcnt lgkmcnt(4)
	v_mfma_f32_32x32x16_bf16 v[0:15], v[68:71], v[194:197], v[0:15]
	v_exp_f32_e32 v246, v110
	s_waitcnt lgkmcnt(2)
	v_mfma_f32_32x32x16_bf16 v[0:15], v[72:75], v[200:203], v[0:15]
	v_exp_f32_e32 v247, v111
	s_waitcnt vmcnt(4)
	s_waitcnt lgkmcnt(0)
	s_barrier
	v_mfma_f32_32x32x16_bf16 v[0:15], v[76:79], v[208:211], v[0:15]
	ds_read_b128 v[64:67], v178
	ds_read_b128 v[68:71], v178 offset:8192
	ds_read_b128 v[190:193], v179
	ds_read_b128 v[194:197], v179 offset:8192
	s_waitcnt lgkmcnt(3)
	v_mfma_f32_32x32x16_bf16 v[96:111], v[64:67], v[136:139], 0
	v_exp_f32_e32 v80, v80
	v_exp_f32_e32 v81, v81
	v_exp_f32_e32 v82, v82
	v_exp_f32_e32 v83, v83
	v_exp_f32_e32 v87, v87
	v_exp_f32_e32 v248, v93
	v_exp_f32_e32 v249, v94
	s_waitcnt lgkmcnt(2)
	v_mfma_f32_32x32x16_bf16 v[64:79], v[68:71], v[136:139], 0
	s_waitcnt lgkmcnt(1)
	v_mfma_f32_32x32x16_bf16 v[96:111], v[190:193], v[140:143], v[96:111]
	s_waitcnt lgkmcnt(0)
	v_mfma_f32_32x32x16_bf16 v[64:79], v[194:197], v[140:143], v[64:79]
	ds_read_b128 v[190:193], v180
	ds_read_b128 v[194:197], v180 offset:8192
	s_waitcnt lgkmcnt(1)
	v_mfma_f32_32x32x16_bf16 v[96:111], v[190:193], v[132:135], v[96:111]
	ds_read_b128 v[190:193], v181
	ds_read_b128 v[200:203], v181 offset:8192
	ds_read_b128 v[204:207], v182
	ds_read_b128 v[208:211], v182 offset:8192
	ds_read_b128 v[212:215], v183
	ds_read_b128 v[216:219], v183 offset:8192
	s_waitcnt lgkmcnt(6)
	v_mfma_f32_32x32x16_bf16 v[64:79], v[194:197], v[132:135], v[64:79]
	ds_read_b128 v[194:197], v184
	ds_read_b128 v[220:223], v184 offset:8192
	ds_read_b128 v[224:227], v185
	ds_read_b128 v[228:231], v185 offset:8192
	s_waitcnt lgkmcnt(9)
	v_mfma_f32_32x32x16_bf16 v[96:111], v[190:193], v[128:131], v[96:111]
	s_cmp_ge_u32 s73, s37
	s_cselect_b64 s[40:41], -1, 0
	s_and_b64 vcc, exec, s[40:41]
	s_cbranch_vccnz .Lat463_b

	s_add_i32 s74, s67, s43
	s_add_u32 s98, s38, s26
	s_addc_u32 s99, s39, s27
	s_mov_b32 m0, s74
	s_add_i32 s43, s72, s43
	global_load_lds_dwordx4 v156, s[98:99]
	s_add_u32 s100, s38, s28
	s_addc_u32 s101, s39, s29
	s_add_i32 m0, s74, 0x2000
	s_nop 0
	global_load_lds_dwordx4 v158, s[98:99]
	s_mov_b32 m0, s43
	s_nop 0
	global_load_lds_dwordx4 v162, s[100:101]
	s_add_i32 m0, s43, 0x2000
	s_nop 0
	global_load_lds_dwordx4 v160, s[100:101]

; #define SBAR() __builtin_amdgcn_sched_barrier(0)
; template <typename TQ> ...
;     ...
;   for (int j = 1; j + 1 < NT; j += 2) {
;     SBAR(); qkt(pB0, pB1, (const bf16*)(K_lds + (j & 3) * (int)SHM_K), qr, r32, hi);
.LBB0_461:
	s_mov_b32 s40, s33
	ds_read_b128 v[80:83], v178 offset:16384
	ds_read_b128 v[84:87], v178 offset:24576
	ds_read_b128 v[198:201], v179 offset:16384
	ds_read_b128 v[202:205], v179 offset:24576
	s_branch .Lat461_a_go

; __device__ __forceinline__ void finishSM(f32x16& p0, f32x16& p1, float alpha, float& l_reg, bf16x8& pa0, bf16x8& pa1, bf16x8& pa2, bf16x8& pa3) {
;   for (int r = 0; r < 16; ++r) p1[r] = __builtin_amdgcn_exp2f(p1[r]);
;   float ps = 0; for (int r = 0; r < 16; ++r) ps += p0[r]; for (int r = 0; r < 16; ++r) ps += p1[r];
;   asm volatile("" : "+v"(ps));
;   l_reg = l_reg * alpha + ps;
;     ...
;   PK4(p0, 0, pa0); PK4(p0, 8, pa1); PK4(p1, 0, pa2); PK4(p1, 8, pa3);
;     ...
; }
; __device__ __forceinline__ void qkt(f32x16& p0, f32x16& p1, const bf16* Ks, const bf16x8* qr, int r32, int hi) {
;   p0 = f32x16{}; p1 = f32x16{};
;   for (int d0 = 0; d0 < 8; ++d0) { int cb = (d0 * 16 + hi * 8) * 2;
;     bf16x8 b0 = *reinterpret_cast<const bf16x8*>((const char*)Ks + KSWZ(r32, cb));
;     bf16x8 b1 = *reinterpret_cast<const bf16x8*>((const char*)Ks + KSWZ(32 + r32, cb));
;     p0 = __builtin_amdgcn_mfma_f32_32x32x16_bf16(b0, qr[d0], p0, 0, 0, 0);
;     p1 = __builtin_amdgcn_mfma_f32_32x32x16_bf16(b1, qr[d0], p1, 0, 0, 0); }
; }
; __device__ __forceinline__ int v_st(int k, int c) { const int kk = k;
;   return ((kk >> 3) * 4 + (c >> 5)) * 512 + ((kk & 7) * 32 + (c & 31)) * 2; }
; __device__ __forceinline__ int v_rd_base(int lane) { return ((lane & 3) << 3) | (((lane >> 2) & 3) << 6) | (((lane >> 4) & 1) << 5) | (((lane >> 5) & 1) << 8); }
; template <int OFF> __device__ __forceinline__ s16x4 tr_read(int vb) {
;   s16x4 r; asm volatile("ds_read_b64_tr_b16 %0, %1 offset:%2" : "=&v"(r) : "v"(vb), "i"(OFF) : "memory"); return r;
; }
; template <int D0> __device__ __forceinline__ void pv_one(f32x16& od, int vb, bf16x8 pa0, bf16x8 pa1, bf16x8 pa2, bf16x8 pa3) {
;   const s16x4 l0 = tr_read<v_rd_off(D0, 0, 0)>(vb), h0 = tr_read<v_rd_off(D0, 0, 1)>(vb), l1 = tr_read<v_rd_off(D0, 1, 0)>(vb), h1 = tr_read<v_rd_off(D0, 1, 1)>(vb);
;   const s16x4 l2 = tr_read<v_rd_off(D0, 2, 0)>(vb), h2 = tr_read<v_rd_off(D0, 2, 1)>(vb), l3 = tr_read<v_rd_off(D0, 3, 0)>(vb), h3 = tr_read<v_rd_off(D0, 3, 1)>(vb);
;   asm volatile("s_waitcnt lgkmcnt(0)" ::: "memory"); SBAR();
;     ...
;   od = __builtin_amdgcn_mfma_f32_32x32x16_bf16(pa0, PK(l0, h0), od, 0, 0, 0);
;   od = __builtin_amdgcn_mfma_f32_32x32x16_bf16(pa1, PK(l1, h1), od, 0, 0, 0);
;   od = __builtin_amdgcn_mfma_f32_32x32x16_bf16(pa2, PK(l2, h2), od, 0, 0, 0);
;   od = __builtin_amdgcn_mfma_f32_32x32x16_bf16(pa3, PK(l3, h3), od, 0, 0, 0);
;     ...
; }
.Lat1365_a_go:
	s_waitcnt lgkmcnt(3)
	v_mfma_f32_32x32x16_bf16 v[96:111], v[80:83], v[136:139], 0
	v_exp_f32_e32 v238, v64
	v_add_f32_e32 v64, v197, v196
	v_add_f32_e32 v64, v193, v64
	v_add_f32_e32 v64, v195, v64
	s_waitcnt lgkmcnt(2)
	v_mfma_f32_32x32x16_bf16 v[80:95], v[84:87], v[136:139], 0
	v_add_f32_e32 v64, v191, v64
	v_add_f32_e32 v64, v194, v64
	v_add_f32_e32 v64, v190, v64
	v_add_f32_e32 v64, v192, v64
	v_add_f32_e32 v64, v169, v64
	v_add_f32_e32 v64, v171, v64
	s_waitcnt lgkmcnt(1)
	v_mfma_f32_32x32x16_bf16 v[96:111], v[198:201], v[140:143], v[96:111]
	v_add_f32_e32 v64, v167, v64
	v_add_f32_e32 v64, v170, v64
	v_add_f32_e32 v64, v165, v64
	v_add_f32_e32 v64, v168, v64
	v_add_f32_e32 v64, v164, v64
	v_add_f32_e32 v64, v166, v64
	v_exp_f32_e32 v239, v68
	s_waitcnt lgkmcnt(0)
	v_mfma_f32_32x32x16_bf16 v[80:95], v[202:205], v[140:143], v[80:95]
	ds_read_b128 v[198:201], v180 offset:16384
	ds_read_b128 v[202:205], v180 offset:24576
	v_add_f32_e32 v64, v238, v64
	v_exp_f32_e32 v240, v69
	v_exp_f32_e32 v241, v70
	v_exp_f32_e32 v242, v71
	s_waitcnt lgkmcnt(1)
	v_mfma_f32_32x32x16_bf16 v[96:111], v[198:201], v[132:135], v[96:111]
	ds_read_b128 v[198:201], v181 offset:16384
	ds_read_b128 v[206:209], v181 offset:24576
	ds_read_b128 v[210:213], v182 offset:16384
	ds_read_b128 v[214:217], v182 offset:24576
	ds_read_b128 v[218:221], v183 offset:16384
	ds_read_b128 v[222:225], v183 offset:24576
	v_exp_f32_e32 v243, v76
	v_exp_f32_e32 v244, v77
	v_exp_f32_e32 v245, v78
	v_exp_f32_e32 v79, v79
	s_waitcnt lgkmcnt(6)
	v_mfma_f32_32x32x16_bf16 v[80:95], v[202:205], v[132:135], v[80:95]
	ds_read_b128 v[202:205], v184 offset:16384
	ds_read_b128 v[226:229], v184 offset:24576
	ds_read_b128 v[230:233], v185 offset:16384
	ds_read_b128 v[234:237], v185 offset:24576
	s_waitcnt lgkmcnt(9)
	v_mfma_f32_32x32x16_bf16 v[96:111], v[198:201], v[128:131], v[96:111]
	v_exp_f32_e32 v199, v65
	v_exp_f32_e32 v200, v66
	v_exp_f32_e32 v201, v67
	v_add_f32_e32 v64, v199, v64
	v_add_f32_e32 v64, v200, v64
	v_add_f32_e32 v64, v201, v64
	s_waitcnt lgkmcnt(8)
	v_mfma_f32_32x32x16_bf16 v[80:95], v[206:209], v[128:131], v[80:95]
	v_exp_f32_e32 v206, v72
	v_add_f32_e32 v64, v239, v64
	v_exp_f32_e32 v207, v73
	v_add_f32_e32 v64, v240, v64
	v_exp_f32_e32 v208, v74
	v_add_f32_e32 v64, v241, v64
	v_exp_f32_e32 v209, v75
	s_waitcnt lgkmcnt(7)
	v_mfma_f32_32x32x16_bf16 v[96:111], v[210:213], v[124:127], v[96:111]
	v_add_f32_e32 v64, v242, v64
	v_add_f32_e32 v64, v206, v64
	v_add_f32_e32 v64, v207, v64
	v_add_f32_e32 v64, v208, v64
	v_add_f32_e32 v64, v209, v64
	v_add_f32_e32 v64, v243, v64
	v_add_f32_e32 v64, v244, v64
	s_waitcnt lgkmcnt(6)
	v_mfma_f32_32x32x16_bf16 v[80:95], v[214:217], v[124:127], v[80:95]
	v_add_f32_e32 v64, v245, v64
	v_add_f32_e32 v198, v79, v64
	v_cvt_pk_bf16_f32 v64, v196, v197
	v_cvt_pk_bf16_f32 v65, v193, v195
	v_cvt_pk_bf16_f32 v66, v191, v194
	v_cvt_pk_bf16_f32 v67, v190, v192
	s_waitcnt lgkmcnt(5)
	v_mfma_f32_32x32x16_bf16 v[96:111], v[218:221], v[120:123], v[96:111]
	v_cvt_pk_bf16_f32 v68, v169, v171
	v_cvt_pk_bf16_f32 v69, v167, v170
	v_cvt_pk_bf16_f32 v70, v165, v168
	v_cvt_pk_bf16_f32 v71, v164, v166
	v_cvt_pk_bf16_f32 v72, v238, v199
	v_cvt_pk_bf16_f32 v73, v200, v201
	v_cvt_pk_bf16_f32 v74, v239, v240
	s_waitcnt lgkmcnt(4)
	v_mfma_f32_32x32x16_bf16 v[80:95], v[222:225], v[120:123], v[80:95]
	v_cvt_pk_bf16_f32 v75, v241, v242
	v_cvt_pk_bf16_f32 v76, v206, v207
	v_cvt_pk_bf16_f32 v77, v208, v209
	v_cvt_pk_bf16_f32 v78, v243, v244
	v_cvt_pk_bf16_f32 v79, v245, v79
	s_waitcnt lgkmcnt(3)
	v_mfma_f32_32x32x16_bf16 v[96:111], v[202:205], v[116:119], v[96:111]
	s_add_i32 s33, s40, 0x8000
	s_and_b32 s43, s33, 0xc000
	ds_read_b64_tr_b16 v[190:191], v176
	ds_read_b64_tr_b16 v[192:193], v176 offset:2048
	ds_read_b64_tr_b16 v[194:195], v176 offset:4096
	ds_read_b64_tr_b16 v[196:197], v176 offset:6144
	s_waitcnt lgkmcnt(6)
	v_mfma_f32_32x32x16_bf16 v[80:95], v[226:229], v[116:119], v[80:95]
	ds_read_b64_tr_b16 v[200:201], v176 offset:8192
	ds_read_b64_tr_b16 v[202:203], v176 offset:10240
	ds_read_b64_tr_b16 v[204:205], v176 offset:12288
	ds_read_b64_tr_b16 v[206:207], v176 offset:14336
	s_add_i32 s73, s40, 0x4000
	s_and_b32 s73, s73, 0xc000
	s_add_u32 s98, s38, s22
	s_addc_u32 s99, s39, s23
	s_add_i32 s41, s66, s73
	s_add_u32 s100, s38, s24
	s_addc_u32 s101, s39, s25
	s_mov_b32 m0, s41
	s_add_i32 s73, s67, s73
	global_load_lds_dwordx4 v156, s[98:99]
	s_waitcnt lgkmcnt(9)
	v_mfma_f32_32x32x16_bf16 v[96:111], v[230:233], v[112:115], v[96:111]
	s_add_i32 m0, s41, 0x2000
	s_nop 0
	global_load_lds_dwordx4 v158, s[98:99]
	s_mov_b32 m0, s73
	s_nop 0
	global_load_lds_dwordx4 v162, s[100:101]
	s_waitcnt lgkmcnt(8)
	v_mfma_f32_32x32x16_bf16 v[80:95], v[234:237], v[112:115], v[80:95]
	s_add_i32 m0, s73, 0x2000
	s_nop 0
	global_load_lds_dwordx4 v160, s[100:101]
	s_nop 0
	s_waitcnt lgkmcnt(6)
	v_mfma_f32_32x32x16_bf16 v[48:63], v[64:67], v[190:193], v[48:63]
	v_exp_f32_e32 v232, v96
	ds_read_b64_tr_b16 v[190:191], v176 offset:512
	ds_read_b64_tr_b16 v[192:193], v176 offset:2560
	s_waitcnt lgkmcnt(6)
; #define SBAR() __builtin_amdgcn_sched_barrier(0)
; #define PUBLISH(n) do { asm volatile("s_waitcnt vmcnt(" #n ")" ::: "memory"); asm volatile("s_waitcnt lgkmcnt(0)" ::: "memory"); __builtin_amdgcn_s_barrier(); SBAR(); } while (0)
; template <int D0> __device__ __forceinline__ void pv_one(f32x16& od, int vb, bf16x8 pa0, bf16x8 pa1, bf16x8 pa2, bf16x8 pa3) {
;   const s16x4 l0 = tr_read<v_rd_off(D0, 0, 0)>(vb), h0 = tr_read<v_rd_off(D0, 0, 1)>(vb), l1 = tr_read<v_rd_off(D0, 1, 0)>(vb), h1 = tr_read<v_rd_off(D0, 1, 1)>(vb);
;   const s16x4 l2 = tr_read<v_rd_off(D0, 2, 0)>(vb), h2 = tr_read<v_rd_off(D0, 2, 1)>(vb), l3 = tr_read<v_rd_off(D0, 3, 0)>(vb), h3 = tr_read<v_rd_off(D0, 3, 1)>(vb);
;   asm volatile("s_waitcnt lgkmcnt(0)" ::: "memory"); SBAR();
;     ...
;   od = __builtin_amdgcn_mfma_f32_32x32x16_bf16(pa0, PK(l0, h0), od, 0, 0, 0);
;   od = __builtin_amdgcn_mfma_f32_32x32x16_bf16(pa1, PK(l1, h1), od, 0, 0, 0);
;   od = __builtin_amdgcn_mfma_f32_32x32x16_bf16(pa2, PK(l2, h2), od, 0, 0, 0);
;   od = __builtin_amdgcn_mfma_f32_32x32x16_bf16(pa3, PK(l3, h3), od, 0, 0, 0);
; template <typename TQ> ...
;     ...
;     SBAR(); qkt(pB0, pB1, (const bf16*)(K_lds + (j & 3) * (int)SHM_K), qr, r32, hi);
;     finishSM(pA0, pA1, alA, l_reg, pa0, pa1, pa2, pa3); SBAR();
;     DMA_TILE(j + 2, (j + 2) & 3); SBAR();
;     pv_d0(o, vb0 + ((j - 1) & 3) * (int)SHM_V, pa0, pa1, pa2, pa3); partialSM<true>(pB0, pB1, m_reg, mnB, alB);
;     PUBLISH(4);
;     SBAR(); qkt(pA0, pA1, (const bf16*)(K_lds + ((j + 1) & 3) * (int)SHM_K), qr, r32, hi);
;     finishSM(pB0, pB1, alB, l_reg, pa0, pa1, pa2, pa3); SBAR();
;     if (j + 3 < NT) { DMA_TILE(j + 3, (j + 3) & 3); } SBAR();
;     pv_d0(o, vb0 + (j & 3) * (int)SHM_V, pa0, pa1, pa2, pa3); partialSM<true>(pA0, pA1, m_reg, mnA, alA);
;     if (j + 3 < NT) { PUBLISH(4); } else { PUBLISH(0); }
	v_mfma_f32_32x32x16_bf16 v[48:63], v[68:71], v[194:197], v[48:63]
	v_exp_f32_e32 v233, v97
	ds_read_b64_tr_b16 v[194:195], v176 offset:4608
	ds_read_b64_tr_b16 v[196:197], v176 offset:6656
	s_waitcnt lgkmcnt(6)
	v_mfma_f32_32x32x16_bf16 v[48:63], v[72:75], v[200:203], v[48:63]
	v_exp_f32_e32 v234, v98
	ds_read_b64_tr_b16 v[200:201], v176 offset:8704
	ds_read_b64_tr_b16 v[202:203], v176 offset:10752
	ds_read_b64_tr_b16 v[208:209], v176 offset:12800
	ds_read_b64_tr_b16 v[210:211], v176 offset:14848
	s_waitcnt lgkmcnt(8)
	v_mfma_f32_32x32x16_bf16 v[48:63], v[76:79], v[204:207], v[48:63]
	v_exp_f32_e32 v235, v99
	s_waitcnt lgkmcnt(6)
	v_mfma_f32_32x32x16_bf16 v[32:47], v[64:67], v[190:193], v[32:47]
	v_exp_f32_e32 v236, v100
	ds_read_b64_tr_b16 v[190:191], v176 offset:1024
	ds_read_b64_tr_b16 v[192:193], v176 offset:3072
	s_waitcnt lgkmcnt(6)
	v_mfma_f32_32x32x16_bf16 v[32:47], v[68:71], v[194:197], v[32:47]
	v_exp_f32_e32 v237, v101
	ds_read_b64_tr_b16 v[194:195], v176 offset:5120
	ds_read_b64_tr_b16 v[196:197], v176 offset:7168
	s_waitcnt lgkmcnt(6)
	v_mfma_f32_32x32x16_bf16 v[32:47], v[72:75], v[200:203], v[32:47]
	v_exp_f32_e32 v238, v102
	ds_read_b64_tr_b16 v[200:201], v176 offset:9216
	ds_read_b64_tr_b16 v[202:203], v176 offset:11264
	ds_read_b64_tr_b16 v[204:205], v176 offset:13312
	ds_read_b64_tr_b16 v[206:207], v176 offset:15360
	s_waitcnt lgkmcnt(8)
	v_mfma_f32_32x32x16_bf16 v[32:47], v[76:79], v[208:211], v[32:47]
	v_exp_f32_e32 v239, v103
	v_exp_f32_e32 v240, v104
	s_waitcnt lgkmcnt(6)
	v_mfma_f32_32x32x16_bf16 v[16:31], v[64:67], v[190:193], v[16:31]
	v_exp_f32_e32 v241, v105
	ds_read_b64_tr_b16 v[190:191], v176 offset:1536
	ds_read_b64_tr_b16 v[192:193], v176 offset:3584
	s_waitcnt lgkmcnt(6)
	v_mfma_f32_32x32x16_bf16 v[16:31], v[68:71], v[194:197], v[16:31]
	v_exp_f32_e32 v242, v106
	ds_read_b64_tr_b16 v[194:195], v176 offset:5632
	ds_read_b64_tr_b16 v[196:197], v176 offset:7680
	s_waitcnt lgkmcnt(6)
	v_mfma_f32_32x32x16_bf16 v[16:31], v[72:75], v[200:203], v[16:31]
	v_exp_f32_e32 v243, v107
	ds_read_b64_tr_b16 v[200:201], v176 offset:9728
	ds_read_b64_tr_b16 v[202:203], v176 offset:11776
	ds_read_b64_tr_b16 v[208:209], v176 offset:13824
	ds_read_b64_tr_b16 v[210:211], v176 offset:15872
	s_waitcnt lgkmcnt(8)
	v_mfma_f32_32x32x16_bf16 v[16:31], v[76:79], v[204:207], v[16:31]
	v_exp_f32_e32 v244, v108
	s_waitcnt lgkmcnt(6)
	v_mfma_f32_32x32x16_bf16 v[0:15], v[64:67], v[190:193], v[0:15]
	v_exp_f32_e32 v245, v109
	s_waitcnt lgkmcnt(4)
	v_mfma_f32_32x32x16_bf16 v[0:15], v[68:71], v[194:197], v[0:15]
	v_exp_f32_e32 v246, v110
	s_waitcnt lgkmcnt(2)
	v_mfma_f32_32x32x16_bf16 v[0:15], v[72:75], v[200:203], v[0:15]
	v_exp_f32_e32 v247, v111
	s_waitcnt vmcnt(4)
	s_waitcnt lgkmcnt(0)
	s_barrier
	v_mfma_f32_32x32x16_bf16 v[0:15], v[76:79], v[208:211], v[0:15]
	ds_read_b128 v[64:67], v178 offset:32768
	ds_read_b128 v[68:71], v178 offset:40960
	ds_read_b128 v[190:193], v179 offset:32768
	ds_read_b128 v[194:197], v179 offset:40960
	s_waitcnt lgkmcnt(3)
	v_mfma_f32_32x32x16_bf16 v[96:111], v[64:67], v[136:139], 0
	v_exp_f32_e32 v80, v80
	v_exp_f32_e32 v81, v81
	v_exp_f32_e32 v82, v82
	v_exp_f32_e32 v83, v83
	v_exp_f32_e32 v87, v87
	v_exp_f32_e32 v248, v93
	v_exp_f32_e32 v249, v94
	s_waitcnt lgkmcnt(2)
	v_mfma_f32_32x32x16_bf16 v[64:79], v[68:71], v[136:139], 0
	s_waitcnt lgkmcnt(1)
	v_mfma_f32_32x32x16_bf16 v[96:111], v[190:193], v[140:143], v[96:111]
	s_waitcnt lgkmcnt(0)
	v_mfma_f32_32x32x16_bf16 v[64:79], v[194:197], v[140:143], v[64:79]
	ds_read_b128 v[190:193], v180 offset:32768
	ds_read_b128 v[194:197], v180 offset:40960
	s_waitcnt lgkmcnt(1)
	v_mfma_f32_32x32x16_bf16 v[96:111], v[190:193], v[132:135], v[96:111]
	ds_read_b128 v[190:193], v181 offset:32768
	ds_read_b128 v[200:203], v181 offset:40960
	ds_read_b128 v[204:207], v182 offset:32768
	ds_read_b128 v[208:211], v182 offset:40960
	ds_read_b128 v[212:215], v183 offset:32768
	ds_read_b128 v[216:219], v183 offset:40960
	s_waitcnt lgkmcnt(6)
	v_mfma_f32_32x32x16_bf16 v[64:79], v[194:197], v[132:135], v[64:79]
	ds_read_b128 v[194:197], v184 offset:32768
	ds_read_b128 v[220:223], v184 offset:40960
	ds_read_b128 v[224:227], v185 offset:32768
	ds_read_b128 v[228:231], v185 offset:40960
	s_waitcnt lgkmcnt(9)
	v_mfma_f32_32x32x16_bf16 v[96:111], v[190:193], v[128:131], v[96:111]
	s_cmp_ge_u32 s72, s37
	s_cselect_b64 s[40:41], -1, 0
	s_and_b64 vcc, exec, s[40:41]
	s_cbranch_vccnz .LBB0_1367
	s_add_i32 s73, s66, s43
	s_add_u32 s98, s38, s26
	s_addc_u32 s99, s39, s27
	s_mov_b32 m0, s73
	s_add_i32 s43, s67, s43
	global_load_lds_dwordx4 v156, s[98:99]
	s_add_u32 s100, s38, s28
	s_addc_u32 s101, s39, s29
	s_add_i32 m0, s73, 0x2000
	s_nop 0
	global_load_lds_dwordx4 v158, s[98:99]
	s_mov_b32 m0, s43
	s_nop 0
	global_load_lds_dwordx4 v162, s[100:101]
	s_add_i32 m0, s43, 0x2000
	s_nop 0
	global_load_lds_dwordx4 v160, s[100:101]

; #define SBAR() __builtin_amdgcn_sched_barrier(0)
; #define PK4(P, BASE, OUT) do { u32x4 w = {cvtpk(P[BASE + 0], P[BASE + 1]), cvtpk(P[BASE + 2], P[BASE + 3]), cvtpk(P[BASE + 4], P[BASE + 5]), cvtpk(P[BASE + 6], P[BASE + 7])}; \
;     OUT = *reinterpret_cast<bf16x8*>(&w); } while (0)
; __device__ __forceinline__ void finishSM(f32x16& p0, f32x16& p1, float alpha, float& l_reg, bf16x8& pa0, bf16x8& pa1, bf16x8& pa2, bf16x8& pa3) {
;   for (int r = 0; r < 16; ++r) p1[r] = __builtin_amdgcn_exp2f(p1[r]);
;   float ps = 0; for (int r = 0; r < 16; ++r) ps += p0[r]; for (int r = 0; r < 16; ++r) ps += p1[r];
;   asm volatile("" : "+v"(ps));
;   l_reg = l_reg * alpha + ps;
;     ...
;   PK4(p0, 0, pa0); PK4(p0, 8, pa1); PK4(p1, 0, pa2); PK4(p1, 8, pa3);
; template <typename TQ> ...
;     ...
;     SBAR(); qkt(pA0, pA1, (const bf16*)(K_lds + ((j + 1) & 3) * (int)SHM_K), qr, r32, hi);
;     finishSM(pB0, pB1, alB, l_reg, pa0, pa1, pa2, pa3); SBAR();
;     if (j + 3 < NT) { DMA_TILE(j + 3, (j + 3) & 3); } SBAR();
;     pv_d0(o, vb0 + (j & 3) * (int)SHM_V, pa0, pa1, pa2, pa3); partialSM<true>(pA0, pA1, m_reg, mnA, alA);
.Lat1365_b:
.Lat1365_b_in:
	s_mov_b32 s40, s33
	ds_read_b128 v[80:83], v178 offset:49152
	ds_read_b128 v[84:87], v178 offset:57344
	ds_read_b128 v[198:201], v179 offset:49152
	ds_read_b128 v[202:205], v179 offset:57344
	v_exp_f32_e32 v196, v96
	v_exp_f32_e32 v197, v97
	v_exp_f32_e32 v193, v98
	v_exp_f32_e32 v195, v99
	v_exp_f32_e32 v191, v100
	v_exp_f32_e32 v194, v101
	v_exp_f32_e32 v190, v102
	v_exp_f32_e32 v192, v103
	v_exp_f32_e32 v169, v104
	v_exp_f32_e32 v171, v105
	v_exp_f32_e32 v167, v106
	v_exp_f32_e32 v170, v107
	v_exp_f32_e32 v165, v108
	v_exp_f32_e32 v168, v109
	v_exp_f32_e32 v164, v110
	v_exp_f32_e32 v166, v111
	s_waitcnt lgkmcnt(3)
	v_mfma_f32_32x32x16_bf16 v[96:111], v[80:83], v[136:139], 0
	v_exp_f32_e32 v238, v64
	v_add_f32_e32 v64, v197, v196
	v_add_f32_e32 v64, v193, v64
	v_add_f32_e32 v64, v195, v64
	s_waitcnt lgkmcnt(2)
	v_mfma_f32_32x32x16_bf16 v[80:95], v[84:87], v[136:139], 0
	v_add_f32_e32 v64, v191, v64
	v_add_f32_e32 v64, v194, v64
	v_add_f32_e32 v64, v190, v64
	v_add_f32_e32 v64, v192, v64
	v_add_f32_e32 v64, v169, v64
	v_add_f32_e32 v64, v171, v64
	s_waitcnt lgkmcnt(1)
	v_mfma_f32_32x32x16_bf16 v[96:111], v[198:201], v[140:143], v[96:111]
	v_add_f32_e32 v64, v167, v64
	v_add_f32_e32 v64, v170, v64
	v_add_f32_e32 v64, v165, v64
	v_add_f32_e32 v64, v168, v64
	v_add_f32_e32 v64, v164, v64
	v_add_f32_e32 v64, v166, v64
	v_exp_f32_e32 v239, v68
	s_waitcnt lgkmcnt(0)
	v_mfma_f32_32x32x16_bf16 v[80:95], v[202:205], v[140:143], v[80:95]
	ds_read_b128 v[198:201], v180 offset:49152
	ds_read_b128 v[202:205], v180 offset:57344
	v_add_f32_e32 v64, v238, v64
	v_exp_f32_e32 v240, v69
	v_exp_f32_e32 v241, v70
	v_exp_f32_e32 v242, v71
	s_waitcnt lgkmcnt(1)
	v_mfma_f32_32x32x16_bf16 v[96:111], v[198:201], v[132:135], v[96:111]
	ds_read_b128 v[198:201], v181 offset:49152
	ds_read_b128 v[206:209], v181 offset:57344
	ds_read_b128 v[210:213], v182 offset:49152
	ds_read_b128 v[214:217], v182 offset:57344
	ds_read_b128 v[218:221], v183 offset:49152
	ds_read_b128 v[222:225], v183 offset:57344
	v_exp_f32_e32 v243, v76
	v_exp_f32_e32 v244, v77
	v_exp_f32_e32 v245, v78
	v_exp_f32_e32 v79, v79
	s_waitcnt lgkmcnt(6)
	v_mfma_f32_32x32x16_bf16 v[80:95], v[202:205], v[132:135], v[80:95]
	ds_read_b128 v[202:205], v184 offset:49152
	ds_read_b128 v[226:229], v184 offset:57344
	ds_read_b128 v[230:233], v185 offset:49152
	ds_read_b128 v[234:237], v185 offset:57344
	s_waitcnt lgkmcnt(9)
	v_mfma_f32_32x32x16_bf16 v[96:111], v[198:201], v[128:131], v[96:111]
	v_exp_f32_e32 v199, v65
	v_exp_f32_e32 v200, v66
	v_exp_f32_e32 v201, v67
	v_add_f32_e32 v64, v199, v64
	v_add_f32_e32 v64, v200, v64
	v_add_f32_e32 v64, v201, v64
	s_waitcnt lgkmcnt(8)
	v_mfma_f32_32x32x16_bf16 v[80:95], v[206:209], v[128:131], v[80:95]
	v_exp_f32_e32 v206, v72
	v_add_f32_e32 v64, v239, v64
	v_exp_f32_e32 v207, v73
	v_add_f32_e32 v64, v240, v64
	v_exp_f32_e32 v208, v74
	v_add_f32_e32 v64, v241, v64
	v_exp_f32_e32 v209, v75
	s_waitcnt lgkmcnt(7)
	v_mfma_f32_32x32x16_bf16 v[96:111], v[210:213], v[124:127], v[96:111]
	v_add_f32_e32 v64, v242, v64
	v_add_f32_e32 v64, v206, v64
	v_add_f32_e32 v64, v207, v64
	v_add_f32_e32 v64, v208, v64
	v_add_f32_e32 v64, v209, v64
	v_add_f32_e32 v64, v243, v64
	v_add_f32_e32 v64, v244, v64
	s_waitcnt lgkmcnt(6)
	v_mfma_f32_32x32x16_bf16 v[80:95], v[214:217], v[124:127], v[80:95]
	v_add_f32_e32 v64, v245, v64
	v_add_f32_e32 v198, v79, v64
	v_cvt_pk_bf16_f32 v64, v196, v197
	v_cvt_pk_bf16_f32 v65, v193, v195
	v_cvt_pk_bf16_f32 v66, v191, v194
	v_cvt_pk_bf16_f32 v67, v190, v192
	s_waitcnt lgkmcnt(5)
	v_mfma_f32_32x32x16_bf16 v[96:111], v[218:221], v[120:123], v[96:111]
	v_cvt_pk_bf16_f32 v68, v169, v171
	v_cvt_pk_bf16_f32 v69, v167, v170
	v_cvt_pk_bf16_f32 v70, v165, v168
	v_cvt_pk_bf16_f32 v71, v164, v166
	v_cvt_pk_bf16_f32 v72, v238, v199
	v_cvt_pk_bf16_f32 v73, v200, v201
	v_cvt_pk_bf16_f32 v74, v239, v240
	s_waitcnt lgkmcnt(4)
	v_mfma_f32_32x32x16_bf16 v[80:95], v[222:225], v[120:123], v[80:95]
	v_cvt_pk_bf16_f32 v75, v241, v242
	v_cvt_pk_bf16_f32 v76, v206, v207
	v_cvt_pk_bf16_f32 v77, v208, v209
	v_cvt_pk_bf16_f32 v78, v243, v244
	v_cvt_pk_bf16_f32 v79, v245, v79
	s_waitcnt lgkmcnt(3)
	v_mfma_f32_32x32x16_bf16 v[96:111], v[202:205], v[116:119], v[96:111]
	s_add_i32 s33, s40, 0x8000
	s_and_b32 s43, s33, 0xc000
	ds_read_b64_tr_b16 v[190:191], v176 offset:32768
	ds_read_b64_tr_b16 v[192:193], v176 offset:34816
	ds_read_b64_tr_b16 v[194:195], v176 offset:36864
	ds_read_b64_tr_b16 v[196:197], v176 offset:38912
	s_waitcnt lgkmcnt(6)
	v_mfma_f32_32x32x16_bf16 v[80:95], v[226:229], v[116:119], v[80:95]
	ds_read_b64_tr_b16 v[200:201], v176 offset:40960
	ds_read_b64_tr_b16 v[202:203], v176 offset:43008
	ds_read_b64_tr_b16 v[204:205], v176 offset:45056
	ds_read_b64_tr_b16 v[206:207], v176 offset:47104
	s_add_i32 s73, s40, 0x4000
	s_and_b32 s73, s73, 0xc000
	s_add_u32 s98, s38, s22
	s_addc_u32 s99, s39, s23
	s_add_i32 s41, s66, s73
	s_add_u32 s100, s38, s24
	s_addc_u32 s101, s39, s25
	s_mov_b32 m0, s41
	s_add_i32 s73, s67, s73
	global_load_lds_dwordx4 v156, s[98:99]
	s_waitcnt lgkmcnt(9)
; #define SBAR() __builtin_amdgcn_sched_barrier(0)
; #define PUBLISH(n) do { asm volatile("s_waitcnt vmcnt(" #n ")" ::: "memory"); asm volatile("s_waitcnt lgkmcnt(0)" ::: "memory"); __builtin_amdgcn_s_barrier(); SBAR(); } while (0)
; template <int D0> __device__ __forceinline__ void pv_one(f32x16& od, int vb, bf16x8 pa0, bf16x8 pa1, bf16x8 pa2, bf16x8 pa3) {
;   const s16x4 l0 = tr_read<v_rd_off(D0, 0, 0)>(vb), h0 = tr_read<v_rd_off(D0, 0, 1)>(vb), l1 = tr_read<v_rd_off(D0, 1, 0)>(vb), h1 = tr_read<v_rd_off(D0, 1, 1)>(vb);
;   const s16x4 l2 = tr_read<v_rd_off(D0, 2, 0)>(vb), h2 = tr_read<v_rd_off(D0, 2, 1)>(vb), l3 = tr_read<v_rd_off(D0, 3, 0)>(vb), h3 = tr_read<v_rd_off(D0, 3, 1)>(vb);
;   asm volatile("s_waitcnt lgkmcnt(0)" ::: "memory"); SBAR();
;     ...
;   od = __builtin_amdgcn_mfma_f32_32x32x16_bf16(pa0, PK(l0, h0), od, 0, 0, 0);
;   od = __builtin_amdgcn_mfma_f32_32x32x16_bf16(pa1, PK(l1, h1), od, 0, 0, 0);
;   od = __builtin_amdgcn_mfma_f32_32x32x16_bf16(pa2, PK(l2, h2), od, 0, 0, 0);
;   od = __builtin_amdgcn_mfma_f32_32x32x16_bf16(pa3, PK(l3, h3), od, 0, 0, 0);
; template <typename TQ> ...
;     ...
;     SBAR(); qkt(pB0, pB1, (const bf16*)(K_lds + (j & 3) * (int)SHM_K), qr, r32, hi);
;     finishSM(pA0, pA1, alA, l_reg, pa0, pa1, pa2, pa3); SBAR();
;     DMA_TILE(j + 2, (j + 2) & 3); SBAR();
;     pv_d0(o, vb0 + ((j - 1) & 3) * (int)SHM_V, pa0, pa1, pa2, pa3); partialSM<true>(pB0, pB1, m_reg, mnB, alB);
;     PUBLISH(4);
;     SBAR(); qkt(pA0, pA1, (const bf16*)(K_lds + ((j + 1) & 3) * (int)SHM_K), qr, r32, hi);
;     finishSM(pB0, pB1, alB, l_reg, pa0, pa1, pa2, pa3); SBAR();
;     if (j + 3 < NT) { DMA_TILE(j + 3, (j + 3) & 3); } SBAR();
;     pv_d0(o, vb0 + (j & 3) * (int)SHM_V, pa0, pa1, pa2, pa3); partialSM<true>(pA0, pA1, m_reg, mnA, alA);
;     if (j + 3 < NT) { PUBLISH(4); } else { PUBLISH(0); }
	v_mfma_f32_32x32x16_bf16 v[96:111], v[230:233], v[112:115], v[96:111]
	s_add_i32 m0, s41, 0x2000
	s_nop 0
	global_load_lds_dwordx4 v158, s[98:99]
	s_mov_b32 m0, s73
	s_nop 0
	global_load_lds_dwordx4 v162, s[100:101]
	s_waitcnt lgkmcnt(8)
	v_mfma_f32_32x32x16_bf16 v[80:95], v[234:237], v[112:115], v[80:95]
	s_add_i32 m0, s73, 0x2000
	s_nop 0
	global_load_lds_dwordx4 v160, s[100:101]
	s_nop 0
	s_waitcnt lgkmcnt(6)
	v_mfma_f32_32x32x16_bf16 v[48:63], v[64:67], v[190:193], v[48:63]
	v_exp_f32_e32 v232, v96
	ds_read_b64_tr_b16 v[190:191], v176 offset:33280
	ds_read_b64_tr_b16 v[192:193], v176 offset:35328
	s_waitcnt lgkmcnt(6)
	v_mfma_f32_32x32x16_bf16 v[48:63], v[68:71], v[194:197], v[48:63]
	v_exp_f32_e32 v233, v97
	ds_read_b64_tr_b16 v[194:195], v176 offset:37376
	ds_read_b64_tr_b16 v[196:197], v176 offset:39424
	s_waitcnt lgkmcnt(6)
	v_mfma_f32_32x32x16_bf16 v[48:63], v[72:75], v[200:203], v[48:63]
	v_exp_f32_e32 v234, v98
	ds_read_b64_tr_b16 v[200:201], v176 offset:41472
	ds_read_b64_tr_b16 v[202:203], v176 offset:43520
	ds_read_b64_tr_b16 v[208:209], v176 offset:45568
	ds_read_b64_tr_b16 v[210:211], v176 offset:47616
	s_waitcnt lgkmcnt(8)
	v_mfma_f32_32x32x16_bf16 v[48:63], v[76:79], v[204:207], v[48:63]
	v_exp_f32_e32 v235, v99
	s_waitcnt lgkmcnt(6)
	v_mfma_f32_32x32x16_bf16 v[32:47], v[64:67], v[190:193], v[32:47]
	v_exp_f32_e32 v236, v100
	ds_read_b64_tr_b16 v[190:191], v176 offset:33792
	ds_read_b64_tr_b16 v[192:193], v176 offset:35840
	s_waitcnt lgkmcnt(6)
	v_mfma_f32_32x32x16_bf16 v[32:47], v[68:71], v[194:197], v[32:47]
	v_exp_f32_e32 v237, v101
	ds_read_b64_tr_b16 v[194:195], v176 offset:37888
	ds_read_b64_tr_b16 v[196:197], v176 offset:39936
	s_waitcnt lgkmcnt(6)
	v_mfma_f32_32x32x16_bf16 v[32:47], v[72:75], v[200:203], v[32:47]
	v_exp_f32_e32 v238, v102
	ds_read_b64_tr_b16 v[200:201], v176 offset:41984
	ds_read_b64_tr_b16 v[202:203], v176 offset:44032
	ds_read_b64_tr_b16 v[204:205], v176 offset:46080
	ds_read_b64_tr_b16 v[206:207], v176 offset:48128
	s_waitcnt lgkmcnt(8)
	v_mfma_f32_32x32x16_bf16 v[32:47], v[76:79], v[208:211], v[32:47]
	v_exp_f32_e32 v239, v103
	v_exp_f32_e32 v240, v104
	s_waitcnt lgkmcnt(6)
	v_mfma_f32_32x32x16_bf16 v[16:31], v[64:67], v[190:193], v[16:31]
	v_exp_f32_e32 v241, v105
	ds_read_b64_tr_b16 v[190:191], v176 offset:34304
	ds_read_b64_tr_b16 v[192:193], v176 offset:36352
	s_waitcnt lgkmcnt(6)
	v_mfma_f32_32x32x16_bf16 v[16:31], v[68:71], v[194:197], v[16:31]
	v_exp_f32_e32 v242, v106
	ds_read_b64_tr_b16 v[194:195], v176 offset:38400
	ds_read_b64_tr_b16 v[196:197], v176 offset:40448
	s_waitcnt lgkmcnt(6)
	v_mfma_f32_32x32x16_bf16 v[16:31], v[72:75], v[200:203], v[16:31]
	v_exp_f32_e32 v243, v107
	ds_read_b64_tr_b16 v[200:201], v176 offset:42496
	ds_read_b64_tr_b16 v[202:203], v176 offset:44544
	ds_read_b64_tr_b16 v[208:209], v176 offset:46592
	ds_read_b64_tr_b16 v[210:211], v176 offset:48640
	s_waitcnt lgkmcnt(8)
	v_mfma_f32_32x32x16_bf16 v[16:31], v[76:79], v[204:207], v[16:31]
	v_exp_f32_e32 v244, v108
	s_waitcnt lgkmcnt(6)
	v_mfma_f32_32x32x16_bf16 v[0:15], v[64:67], v[190:193], v[0:15]
	v_exp_f32_e32 v245, v109
	s_waitcnt lgkmcnt(4)
	v_mfma_f32_32x32x16_bf16 v[0:15], v[68:71], v[194:197], v[0:15]
	v_exp_f32_e32 v246, v110
	s_waitcnt lgkmcnt(2)
	v_mfma_f32_32x32x16_bf16 v[0:15], v[72:75], v[200:203], v[0:15]
	v_exp_f32_e32 v247, v111
	s_waitcnt vmcnt(4)
	s_waitcnt lgkmcnt(0)
	s_barrier
	v_mfma_f32_32x32x16_bf16 v[0:15], v[76:79], v[208:211], v[0:15]
	ds_read_b128 v[64:67], v178
	ds_read_b128 v[68:71], v178 offset:8192
	ds_read_b128 v[190:193], v179
	ds_read_b128 v[194:197], v179 offset:8192
	s_waitcnt lgkmcnt(3)
	v_mfma_f32_32x32x16_bf16 v[96:111], v[64:67], v[136:139], 0
	v_exp_f32_e32 v80, v80
	v_exp_f32_e32 v81, v81
	v_exp_f32_e32 v82, v82
	v_exp_f32_e32 v83, v83
	v_exp_f32_e32 v87, v87
	v_exp_f32_e32 v248, v93
	v_exp_f32_e32 v249, v94
	s_waitcnt lgkmcnt(2)
	v_mfma_f32_32x32x16_bf16 v[64:79], v[68:71], v[136:139], 0
	s_waitcnt lgkmcnt(1)
	v_mfma_f32_32x32x16_bf16 v[96:111], v[190:193], v[140:143], v[96:111]
	s_waitcnt lgkmcnt(0)
	v_mfma_f32_32x32x16_bf16 v[64:79], v[194:197], v[140:143], v[64:79]
	ds_read_b128 v[190:193], v180
	ds_read_b128 v[194:197], v180 offset:8192
	s_waitcnt lgkmcnt(1)
	v_mfma_f32_32x32x16_bf16 v[96:111], v[190:193], v[132:135], v[96:111]
	ds_read_b128 v[190:193], v181
	ds_read_b128 v[200:203], v181 offset:8192
	ds_read_b128 v[204:207], v182
	ds_read_b128 v[208:211], v182 offset:8192
	ds_read_b128 v[212:215], v183
	ds_read_b128 v[216:219], v183 offset:8192
	s_waitcnt lgkmcnt(6)
	v_mfma_f32_32x32x16_bf16 v[64:79], v[194:197], v[132:135], v[64:79]
	ds_read_b128 v[194:197], v184
	ds_read_b128 v[220:223], v184 offset:8192
	ds_read_b128 v[224:227], v185
	ds_read_b128 v[228:231], v185 offset:8192
	s_waitcnt lgkmcnt(9)
	v_mfma_f32_32x32x16_bf16 v[96:111], v[190:193], v[128:131], v[96:111]
	s_cmp_ge_u32 s72, s37
	s_cselect_b64 s[40:41], -1, 0
	s_and_b64 vcc, exec, s[40:41]
	s_cbranch_vccnz .Lat1367_b

	s_add_i32 s73, s66, s43
	s_add_u32 s98, s38, s26
	s_addc_u32 s99, s39, s27
	s_mov_b32 m0, s73
	s_add_i32 s43, s67, s43
	global_load_lds_dwordx4 v156, s[98:99]
	s_add_u32 s100, s38, s28
	s_addc_u32 s101, s39, s29
	s_add_i32 m0, s73, 0x2000
	s_nop 0
	global_load_lds_dwordx4 v158, s[98:99]
	s_mov_b32 m0, s43
	s_nop 0
	global_load_lds_dwordx4 v162, s[100:101]
	s_add_i32 m0, s43, 0x2000
	s_nop 0
	global_load_lds_dwordx4 v160, s[100:101]
